# as previous plus: common path skips the redundant alpha<1 rescale test at the end of each attention tile (alpha is 1.0 unless the rare max-raise path ran)
# baseline (speedup 1.0000x reference)
; __device__ __forceinline__ void finishSM(f32x16& p0, f32x16& p1, float alpha, float& l_reg, bf16x8& pa0, bf16x8& pa1, bf16x8& pa2, bf16x8& pa3) {
; #pragma unroll
;   for (int r = 0; r < 16; ++r) p1[r] = __builtin_amdgcn_exp2f(p1[r]);
;   float ps = 0;
; #pragma unroll
;   for (int r = 0; r < 16; ++r) ps += p0[r];
; #pragma unroll
;   for (int r = 0; r < 16; ++r) ps += p1[r];
;   { auto rr = __builtin_amdgcn_permlane32_swap(__float_as_uint(ps), __float_as_uint(ps), false, false);
;     ps = __uint_as_float(rr[0]) + __uint_as_float(rr[1]); }
;   l_reg = l_reg * alpha + ps;
;     ...
;   PK4(p0, 0, pa0); PK4(p0, 8, pa1); PK4(p1, 0, pa2); PK4(p1, 8, pa3);
;     ...
; }
; template <int NQ> __device__ __forceinline__ void qkt(f32x16& p0, f32x16& p1, const char* Ks, const bf16x8* qr, int r32, int hi, int kcolB) {
;   p0 = f32x16{}; p1 = f32x16{};
; #pragma unroll
;   for (int d0 = 0; d0 < NQ; ++d0) { const int cb = kcolB + (d0 * 16 + hi * 8) * 2;
;     bf16x8 b0 = *reinterpret_cast<const bf16x8*>(Ks + KSWZ(r32, cb));
;     bf16x8 b1 = *reinterpret_cast<const bf16x8*>(Ks + KSWZ(32 + r32, cb));
;     p0 = __builtin_amdgcn_mfma_f32_32x32x16_bf16(b0, qr[d0], p0, 0, 0, 0);
;     p1 = __builtin_amdgcn_mfma_f32_32x32x16_bf16(b1, qr[d0], p1, 0, 0, 0); }
; }
; __device__ __forceinline__ void qkt0(f32x16& p0, f32x16& p1, const char* Ks, const char* Qs, int r32, int hi, int kcolB, const f32x16& init) {
; #pragma unroll
;   for (int d0 = 0; d0 < 4; ++d0) { const int cb = kcolB + (d0 * 16 + hi * 8) * 2;
;     bf16x8 b0 = *reinterpret_cast<const bf16x8*>(Ks + KSWZ(r32, cb));
;     bf16x8 b1 = *reinterpret_cast<const bf16x8*>(Ks + KSWZ(32 + r32, cb));
;     bf16x8 qf = *reinterpret_cast<const bf16x8*>(Qs + r32 * 128 + (((2 * d0 + hi) ^ (r32 & 7)) << 4));
;     if (d0 == 0) { p0 = __builtin_amdgcn_mfma_f32_32x32x16_bf16(b0, qf, init, 0, 0, 0); p1 = __builtin_amdgcn_mfma_f32_32x32x16_bf16(b1, qf, init, 0, 0, 0); }
;     else { p0 = __builtin_amdgcn_mfma_f32_32x32x16_bf16(b0, qf, p0, 0, 0, 0); p1 = __builtin_amdgcn_mfma_f32_32x32x16_bf16(b1, qf, p1, 0, 0, 0); } }
; }
.Lstag_a:
	s_add_i32 s34, s59, 0
	v_add_u32_e32 v112, s34, v193
	v_add_u32_e32 v116, s34, v194
	ds_read_b128 v[112:115], v112 offset:16384
	ds_read_b128 v[202:205], v181
	ds_read_b128 v[206:209], v180
	ds_read_b128 v[210:213], v116 offset:16384
	v_exp_f32_e32 v234, v96
	v_add_f32_e32 v96, 0, v161
	s_waitcnt lgkmcnt(2)
	v_mfma_f32_32x32x16_bf16 v[128:143], v[112:115], v[202:205], v[80:95]
	v_add_u32_e32 v112, s34, v197
	v_add_u32_e32 v113, s34, v195
	v_add_f32_e32 v96, v163, v96
	ds_read_b128 v[214:217], v112 offset:16384
	ds_read_b128 v[218:221], v113 offset:16384
	v_add_f32_e32 v96, v159, v96
	v_add_f32_e32 v96, v162, v96
	v_add_f32_e32 v96, v157, v96
	s_waitcnt lgkmcnt(2)
	v_mfma_f32_32x32x16_bf16 v[112:127], v[210:213], v[202:205], v[80:95]
	v_add_f32_e32 v96, v160, v96
	v_add_f32_e32 v96, v156, v96
	v_add_f32_e32 v96, v158, v96
	v_add_f32_e32 v96, v153, v96
	v_add_f32_e32 v96, v155, v96
	v_add_f32_e32 v96, v151, v96
	v_add_f32_e32 v96, v154, v96
	s_waitcnt lgkmcnt(0)
	v_mfma_f32_32x32x16_bf16 v[128:143], v[218:221], v[206:209], v[128:143]
	v_add_f32_e32 v96, v149, v96
	v_add_u32_e32 v201, s34, v199
	v_add_u32_e32 v210, s34, v196
	v_exp_f32_e32 v235, v97
	v_add_f32_e32 v96, v152, v96
	ds_read_b128 v[202:205], v201 offset:16384
	ds_read_b128 v[210:213], v210 offset:16384
	ds_read_b128 v[222:225], v179
	ds_read_b128 v[226:229], v178
	v_exp_f32_e32 v236, v98
	v_mfma_f32_32x32x16_bf16 v[112:127], v[214:217], v[206:209], v[112:127]
	v_add_f32_e32 v96, v148, v96
	v_exp_f32_e32 v237, v99
	v_add_f32_e32 v96, v150, v96
	v_exp_f32_e32 v238, v100
	v_add_f32_e32 v96, v234, v96
	v_exp_f32_e32 v239, v101
	v_add_f32_e32 v96, v235, v96
	v_exp_f32_e32 v206, v102
	s_waitcnt lgkmcnt(1)
	v_mfma_f32_32x32x16_bf16 v[128:143], v[210:213], v[222:225], v[128:143]
	v_add_f32_e32 v96, v236, v96
	v_exp_f32_e32 v207, v103
	v_add_f32_e32 v96, v237, v96
	v_add_u32_e32 v201, s34, v200
	v_add_u32_e32 v230, s34, v198
	v_exp_f32_e32 v208, v104
	v_add_f32_e32 v96, v238, v96
	v_mfma_f32_32x32x16_bf16 v[112:127], v[202:205], v[222:225], v[112:127]
	ds_read_b128 v[218:221], v201 offset:16384
	ds_read_b128 v[230:233], v230 offset:16384
	v_exp_f32_e32 v209, v105
	v_add_f32_e32 v96, v239, v96
	v_exp_f32_e32 v214, v106
	v_add_f32_e32 v96, v206, v96
	v_exp_f32_e32 v215, v107
	v_add_f32_e32 v96, v207, v96
	v_exp_f32_e32 v216, v108
	v_add_f32_e32 v96, v208, v96
	v_exp_f32_e32 v210, v109
	v_add_f32_e32 v96, v209, v96
	v_exp_f32_e32 v211, v110
	s_waitcnt lgkmcnt(0)
	v_mfma_f32_32x32x16_bf16 v[128:143], v[230:233], v[226:229], v[128:143]
	v_add_f32_e32 v96, v214, v96
	v_exp_f32_e32 v111, v111
	v_add_f32_e32 v96, v215, v96
	v_add_f32_e32 v96, v216, v96
	v_add_f32_e32 v96, v210, v96
	v_add_f32_e32 v96, v211, v96
	v_add_f32_e32 v201, v111, v96
	v_mfma_f32_32x32x16_bf16 v[112:127], v[218:221], v[226:229], v[112:127]
	v_mov_b32_e32 v202, v201
	s_nop 1
	v_permlane32_swap_b32_e32 v201, v202
	v_cvt_pk_bf16_f32 v96, v161, v163
	v_cvt_pk_bf16_f32 v97, v159, v162
	v_cvt_pk_bf16_f32 v98, v157, v160
	v_cvt_pk_bf16_f32 v99, v156, v158
	v_cvt_pk_bf16_f32 v100, v153, v155
	v_cvt_pk_bf16_f32 v101, v151, v154
	v_cvt_pk_bf16_f32 v102, v149, v152
	v_cvt_pk_bf16_f32 v103, v148, v150
	v_cvt_pk_bf16_f32 v104, v234, v235
	v_cvt_pk_bf16_f32 v105, v236, v237
	v_cvt_pk_bf16_f32 v106, v238, v239
	v_cvt_pk_bf16_f32 v107, v206, v207
	v_cvt_pk_bf16_f32 v108, v208, v209
	v_cvt_pk_bf16_f32 v109, v214, v215
	v_cvt_pk_bf16_f32 v110, v216, v210
	v_cvt_pk_bf16_f32 v111, v211, v111
	s_nop 0
	v_permlane32_swap_b32_e32 v96, v98
	v_permlane32_swap_b32_e32 v97, v99
	v_permlane32_swap_b32_e32 v100, v102
	v_permlane32_swap_b32_e32 v101, v103
	v_permlane32_swap_b32_e32 v104, v106
	v_permlane32_swap_b32_e32 v105, v107
	v_permlane32_swap_b32_e32 v108, v110
	v_permlane32_swap_b32_e32 v109, v111
	v_add_u32_e32 v203, s36, v175
	ds_read_b64_tr_b16 v[148:149], v203 offset:0
	ds_read_b64_tr_b16 v[150:151], v203 offset:0x800
	ds_read_b64_tr_b16 v[152:153], v203 offset:0x1000
	ds_read_b64_tr_b16 v[154:155], v203 offset:0x1800
	ds_read_b64_tr_b16 v[156:157], v203 offset:0x2000
	ds_read_b64_tr_b16 v[158:159], v203 offset:0x2800
	ds_read_b64_tr_b16 v[160:161], v203 offset:0x3000
	ds_read_b64_tr_b16 v[162:163], v203 offset:0x3800
	s_add_i32 s34, s58, 1
	s_waitcnt lgkmcnt(0)
; __device__ __forceinline__ void pv_d0(f32x16* o, int vb, bf16x8 pa0, bf16x8 pa1, bf16x8 pa2, bf16x8 pa3) {
;   s16x4 la[4], ha[4];
;   rd8<0>(la, ha, vb); WAITDEP(0, la, ha); mma4(o[0], la, ha, pa0, pa1, pa2, pa3);
;   rd8<1>(la, ha, vb); WAITDEP(0, la, ha); mma4(o[1], la, ha, pa0, pa1, pa2, pa3);
;   rd8<2>(la, ha, vb); WAITDEP(0, la, ha); mma4(o[2], la, ha, pa0, pa1, pa2, pa3);
;   rd8<3>(la, ha, vb); WAITDEP(0, la, ha); mma4(o[3], la, ha, pa0, pa1, pa2, pa3);
; }
; template <int MODE>
; __device__ __forceinline__ void attn_unit(bf16r* P0, const bf16r* __restrict__ PKV, int rowbase, int seqL, int h, int blk, float lam,
;                                           const float* __restrict__ subg, const float* __restrict__ tsrc, char* lds) {
;   constexpr int NQ = (MODE == 0) ? 4 : 8;
;   int tid_ = threadIdx.x; asm volatile("" : "+v"(tid_));
;   const int tid = tid_, wid = __builtin_amdgcn_readfirstlane(tid >> 6), lane = tid & 63, r32 = lane & 31, hi = lane >> 5;
;   float* ws = (float*)(lds + OFF_WS) + wid * 64; float* li_l = ws; float* al_l = ws + 32;
;   float* tb = (float*)(lds + OFF_TB);
;   int qrow, kcolB, tbase, NT, colbase, gr = 0, rs = 0, qc = 0, cmap = 0;
;   float bL = 0.f, bR = 0.f;
;   if constexpr (MODE == 0) {
;     cmap = wid >> 2; qrow = blk * 128 + (wid & 3) * 32; kcolB = cmap * 128; tbase = 0; NT = seqL / KVBLK; colbase = h * 128;
;     bL = tsrc[15 * 8 + h] * LOG2E; bR = tsrc[31 * 8 + h] * LOG2E;
;     { const int rel = tid - 256, n = rel < 0 ? -rel : rel;
;       int bk = n < 8 ? n : min(15, 8 + (31 - __clz((n * n) >> 6))); if (rel > 0) bk += 16;
;       tb[tid] = tsrc[bk * 8 + h] * LOG2E; }
;   } else {
;     const int rows = seqL / 64; qrow = blk * 256 + wid * 32; kcolB = 0; colbase = 1024 + h * 128; NT = 12;
;     const int rs0 = min(max(blk * 4 - 4, 0), rows - 8); tbase = min(rs0, rows - 12);
;     gr = blk * 4 + (wid >> 1); rs = min(max(gr - 4, 0), rows - 8); qc = (wid & 1) * 32 + r32;
;     for (int i = tid; i < 15 * 128; i += 512) { const int dr = i >> 7, dc = (i & 127) - 48; tb[i] = (dc >= 0 && dc < 31) ? tsrc[(h * 15 + dr) * 31 + dc] * LOG2E : 0.f; }
;   }
;   const bf16r* Qw = P0 + (size_t)(rowbase + qrow + r32) * LD + colbase + (MODE == 0 ? cmap * 64 : 0) + hi * 8;
;   const bf16r* Kh = PKV + (size_t)rowbase * LD + h * 128; const bf16r* Vh = Kh + 1024;
;   float m_reg = -1e30f, l_reg = 0; f32x16 o[4] = {};
	s_add_i32 s60, s37, 0
	v_mfma_f32_32x32x16_bf16 v[64:79], v[96:99], v[148:151], v[64:79]
	ds_read_b64_tr_b16 v[148:149], v203 offset:0x200
	ds_read_b64_tr_b16 v[150:151], v203 offset:0xa00
	ds_read_b64_tr_b16 v[204:205], v203 offset:0x1200
	ds_read_b64_tr_b16 v[206:207], v203 offset:0x1a00
	ds_read_b64_tr_b16 v[208:209], v203 offset:0x2200
	ds_read_b64_tr_b16 v[210:211], v203 offset:0x2a00
	ds_read_b64_tr_b16 v[212:213], v203 offset:0x3200
	v_mfma_f32_32x32x16_bf16 v[64:79], v[100:103], v[152:155], v[64:79]
	ds_read_b64_tr_b16 v[214:215], v203 offset:0x3a00
	s_min_i32 s34, s34, s39
	s_waitcnt lgkmcnt(0)
	s_cmp_ge_i32 s34, s56
	s_cselect_b32 s35, s57, 0
	s_add_i32 s35, s35, s34
	s_lshl_b32 s34, s35, 6
	v_mfma_f32_32x32x16_bf16 v[64:79], v[104:107], v[156:159], v[64:79]
	v_mfma_f32_32x32x16_bf16 v[48:63], v[96:99], v[148:151], v[48:63]
	ds_read_b64_tr_b16 v[148:149], v203 offset:0x400
	ds_read_b64_tr_b16 v[150:151], v203 offset:0xc00
	ds_read_b64_tr_b16 v[152:153], v203 offset:0x1400
	ds_read_b64_tr_b16 v[154:155], v203 offset:0x1c00
	v_mfma_f32_32x32x16_bf16 v[64:79], v[108:111], v[160:163], v[64:79]
	ds_read_b64_tr_b16 v[160:161], v203 offset:0x2400
	ds_read_b64_tr_b16 v[162:163], v203 offset:0x2c00
	v_mfma_f32_32x32x16_bf16 v[48:63], v[100:103], v[204:207], v[48:63]
	ds_read_b64_tr_b16 v[204:205], v203 offset:0x3400
	ds_read_b64_tr_b16 v[206:207], v203 offset:0x3c00
	s_nop 0
	s_waitcnt lgkmcnt(0)
	ds_read_b64_tr_b16 v[216:217], v203 offset:0x600
	ds_read_b64_tr_b16 v[218:219], v203 offset:0xe00
	s_nop 0
	v_mfma_f32_32x32x16_bf16 v[32:47], v[96:99], v[148:151], v[32:47]
	s_lshl_b32 s98, s34, 12
	s_add_u32 s98, s30, s98
	s_addc_u32 s99, s31, 0
	v_mfma_f32_32x32x16_bf16 v[48:63], v[104:107], v[208:211], v[48:63]
	ds_read_b64_tr_b16 v[208:209], v203 offset:0x1600
	ds_read_b64_tr_b16 v[210:211], v203 offset:0x1e00
	ds_read_b64_tr_b16 v[220:221], v203 offset:0x2600
	ds_read_b64_tr_b16 v[222:223], v203 offset:0x2e00
	ds_read_b64_tr_b16 v[224:225], v203 offset:0x3600
	ds_read_b64_tr_b16 v[226:227], v203 offset:0x3e00
	v_mfma_f32_32x32x16_bf16 v[32:47], v[100:103], v[152:155], v[32:47]
	s_waitcnt lgkmcnt(0)
	s_waitcnt vmcnt(0)
	global_load_dwordx4 v[156:159], v252, s[98:99] offset:2048
	s_nop 0
	global_load_dwordx4 v[148:151], v252, s[98:99]
	v_add_u32_e32 v203, s60, v183
	v_mfma_f32_32x32x16_bf16 v[32:47], v[104:107], v[160:163], v[32:47]
	global_load_dwordx4 v[160:163], v253, s[98:99] offset:2048
	s_nop 0
	global_load_dwordx4 v[152:155], v253, s[98:99]
	ds_write_b128 v203, v[6:9]
	v_add_u32_e32 v6, s60, v189
	ds_write_b128 v6, v[144:147]
	v_add_u32_e32 v6, s60, v190
	ds_write_b128 v6, v[2:5] offset:16384
	v_add_u32_e32 v2, s60, v191
	v_mfma_f32_32x32x16_bf16 v[16:31], v[96:99], v[216:219], v[16:31]
	ds_write_b128 v2, v[10:13] offset:16384
	v_max_f32_e32 v2, v128, v129
	v_max3_f32 v2, v2, v130, v131
	v_max3_f32 v2, v2, v132, v133
	v_max3_f32 v2, v2, v134, v135
	v_mfma_f32_32x32x16_bf16 v[16:31], v[100:103], v[208:211], v[16:31]
	v_max3_f32 v2, v2, v136, v137
	v_max3_f32 v2, v2, v138, v139
	v_max3_f32 v2, v2, v140, v141
	v_max3_f32 v2, v2, v142, v143
	v_max3_f32 v2, v2, v112, v113
	v_max3_f32 v2, v2, v114, v115
	v_max3_f32 v2, v2, v116, v117
	v_mfma_f32_32x32x16_bf16 v[16:31], v[104:107], v[220:223], v[16:31]
	v_max3_f32 v2, v2, v118, v119
	v_max3_f32 v2, v2, v120, v121
	v_max3_f32 v2, v2, v122, v123
	v_max3_f32 v2, v2, v124, v125
	v_max3_f32 v2, v2, v126, v127
	v_mov_b32_e32 v3, v2
	s_nop 1
	v_permlane32_swap_b32_e32 v2, v3
	v_mfma_f32_32x32x16_bf16 v[48:63], v[108:111], v[212:215], v[48:63]
	v_max_f32_e32 v2, v2, v3
	v_cmp_ge_f32_e32 vcc, s49, v2
	s_cmp_eq_u64 vcc, exec
	v_mov_b32_e32 v203, 1.0
	v_mfma_f32_32x32x16_bf16 v[32:47], v[108:111], v[204:207], v[32:47]
	v_mfma_f32_32x32x16_bf16 v[16:31], v[108:111], v[224:227], v[16:31]
	s_cbranch_scc0 .LBB0_229
	s_branch .LBB0_220

; __device__ __forceinline__ void finishSM(f32x16& p0, f32x16& p1, float alpha, float& l_reg, bf16x8& pa0, bf16x8& pa1, bf16x8& pa2, bf16x8& pa3) {
; #pragma unroll
;   for (int r = 0; r < 16; ++r) p1[r] = __builtin_amdgcn_exp2f(p1[r]);
;   float ps = 0;
; #pragma unroll
;   for (int r = 0; r < 16; ++r) ps += p0[r];
; #pragma unroll
;   for (int r = 0; r < 16; ++r) ps += p1[r];
;   { auto rr = __builtin_amdgcn_permlane32_swap(__float_as_uint(ps), __float_as_uint(ps), false, false);
;     ps = __uint_as_float(rr[0]) + __uint_as_float(rr[1]); }
;   l_reg = l_reg * alpha + ps;
;     ...
;   PK4(p0, 0, pa0); PK4(p0, 8, pa1); PK4(p1, 0, pa2); PK4(p1, 8, pa3);
;     ...
; }
; template <int NQ> __device__ __forceinline__ void qkt(f32x16& p0, f32x16& p1, const char* Ks, const bf16x8* qr, int r32, int hi, int kcolB) {
;   p0 = f32x16{}; p1 = f32x16{};
; #pragma unroll
;   for (int d0 = 0; d0 < NQ; ++d0) { const int cb = kcolB + (d0 * 16 + hi * 8) * 2;
;     bf16x8 b0 = *reinterpret_cast<const bf16x8*>(Ks + KSWZ(r32, cb));
;     bf16x8 b1 = *reinterpret_cast<const bf16x8*>(Ks + KSWZ(32 + r32, cb));
;     p0 = __builtin_amdgcn_mfma_f32_32x32x16_bf16(b0, qr[d0], p0, 0, 0, 0);
;     p1 = __builtin_amdgcn_mfma_f32_32x32x16_bf16(b1, qr[d0], p1, 0, 0, 0); }
; }
; __device__ __forceinline__ void qkt0(f32x16& p0, f32x16& p1, const char* Ks, const char* Qs, int r32, int hi, int kcolB, const f32x16& init) {
; #pragma unroll
;   for (int d0 = 0; d0 < 4; ++d0) { const int cb = kcolB + (d0 * 16 + hi * 8) * 2;
;     bf16x8 b0 = *reinterpret_cast<const bf16x8*>(Ks + KSWZ(r32, cb));
;     bf16x8 b1 = *reinterpret_cast<const bf16x8*>(Ks + KSWZ(32 + r32, cb));
;     bf16x8 qf = *reinterpret_cast<const bf16x8*>(Qs + r32 * 128 + (((2 * d0 + hi) ^ (r32 & 7)) << 4));
;     if (d0 == 0) { p0 = __builtin_amdgcn_mfma_f32_32x32x16_bf16(b0, qf, init, 0, 0, 0); p1 = __builtin_amdgcn_mfma_f32_32x32x16_bf16(b1, qf, init, 0, 0, 0); }
;     else { p0 = __builtin_amdgcn_mfma_f32_32x32x16_bf16(b0, qf, p0, 0, 0, 0); p1 = __builtin_amdgcn_mfma_f32_32x32x16_bf16(b1, qf, p1, 0, 0, 0); } }
; }
.Lstag_b:
	v_exp_f32_e32 v224, v128
	v_exp_f32_e32 v225, v129
	v_exp_f32_e32 v226, v130
	v_exp_f32_e32 v227, v131
	v_exp_f32_e32 v228, v132
	v_exp_f32_e32 v229, v133
	v_exp_f32_e32 v230, v134
	v_exp_f32_e32 v231, v135
	v_exp_f32_e32 v232, v136
	v_exp_f32_e32 v233, v137
	v_exp_f32_e32 v234, v138
	v_exp_f32_e32 v235, v139
	v_exp_f32_e32 v236, v140
	v_exp_f32_e32 v237, v141
	v_exp_f32_e32 v238, v142
	v_exp_f32_e32 v239, v143
	v_add_u32_e32 v2, s60, v193
	ds_read_b128 v[2:5], v2 offset:16384
	ds_read_b128 v[6:9], v181
	v_add_u32_e32 v96, s60, v194
	ds_read_b128 v[10:13], v180
	v_add_u32_e32 v97, s60, v195
	v_add_u32_e32 v208, s60, v199
	s_waitcnt lgkmcnt(1)
	v_mfma_f32_32x32x16_bf16 v[128:143], v[2:5], v[6:9], v[80:95]
	ds_read_b128 v[2:5], v96 offset:16384
	v_add_u32_e32 v96, s60, v197
	ds_read_b128 v[144:147], v96 offset:16384
	ds_read_b128 v[204:207], v97 offset:16384
	v_add_u32_e32 v209, s60, v196
	v_exp_f32_e32 v240, v114
	v_exp_f32_e32 v241, v115
	v_exp_f32_e32 v242, v116
	s_waitcnt lgkmcnt(0)
	v_mfma_f32_32x32x16_bf16 v[128:143], v[204:207], v[10:13], v[128:143]
	v_exp_f32_e32 v206, v112
	v_exp_f32_e32 v207, v113
	v_exp_f32_e32 v243, v117
	v_exp_f32_e32 v244, v118
	v_add_u32_e32 v216, s60, v200
	v_add_u32_e32 v220, s60, v198
	v_mfma_f32_32x32x16_bf16 v[96:111], v[2:5], v[6:9], v[80:95]
	ds_read_b128 v[2:5], v208 offset:16384
	ds_read_b128 v[6:9], v209 offset:16384
	ds_read_b128 v[208:211], v179
	ds_read_b128 v[212:215], v178
	ds_read_b128 v[216:219], v216 offset:16384
	ds_read_b128 v[220:223], v220 offset:16384
	v_cvt_pk_bf16_f32 v116, v224, v225
	v_cvt_pk_bf16_f32 v117, v226, v227
	v_cvt_pk_bf16_f32 v118, v228, v229
	s_nop 0
	v_permlane32_swap_b32_e32 v116, v118
	v_mfma_f32_32x32x16_bf16 v[96:111], v[144:147], v[10:13], v[96:111]
	v_exp_f32_e32 v10, v119
	v_exp_f32_e32 v11, v120
	v_exp_f32_e32 v12, v121
	v_exp_f32_e32 v13, v122
	v_exp_f32_e32 v144, v123
	v_exp_f32_e32 v145, v124
	v_exp_f32_e32 v146, v125
	s_waitcnt lgkmcnt(3)
	v_mfma_f32_32x32x16_bf16 v[128:143], v[6:9], v[208:211], v[128:143]
	v_add_f32_e32 v8, 0, v224
	v_add_f32_e32 v8, v225, v8
	v_add_f32_e32 v8, v226, v8
	v_add_f32_e32 v8, v227, v8
	v_add_f32_e32 v8, v228, v8
	v_exp_f32_e32 v6, v126
	v_exp_f32_e32 v7, v127
	v_mfma_f32_32x32x16_bf16 v[96:111], v[2:5], v[208:211], v[96:111]
	v_add_f32_e32 v2, v229, v8
	v_add_f32_e32 v2, v230, v2
	v_add_f32_e32 v2, v231, v2
	v_add_f32_e32 v2, v232, v2
	v_add_f32_e32 v2, v233, v2
	v_add_f32_e32 v2, v234, v2
	v_add_f32_e32 v2, v235, v2
	v_add_f32_e32 v2, v236, v2
	v_add_f32_e32 v2, v237, v2
	v_add_f32_e32 v2, v238, v2
	v_add_f32_e32 v2, v239, v2
	v_add_f32_e32 v2, v206, v2
	v_add_f32_e32 v2, v207, v2
	v_add_f32_e32 v2, v240, v2
	v_add_f32_e32 v2, v241, v2
	v_add_f32_e32 v2, v242, v2
	v_add_f32_e32 v2, v243, v2
	v_add_f32_e32 v2, v244, v2
	v_add_f32_e32 v2, v10, v2
	v_add_f32_e32 v2, v11, v2
	v_add_f32_e32 v2, v12, v2
	s_waitcnt lgkmcnt(0)
	v_mfma_f32_32x32x16_bf16 v[128:143], v[220:223], v[212:215], v[128:143]
	v_add_f32_e32 v2, v13, v2
	v_add_f32_e32 v2, v144, v2
	v_add_f32_e32 v2, v145, v2
	v_add_f32_e32 v2, v146, v2
	v_add_f32_e32 v2, v6, v2
	v_add_f32_e32 v204, v7, v2
	v_mov_b32_e32 v205, v204
	v_mfma_f32_32x32x16_bf16 v[96:111], v[216:219], v[212:215], v[96:111]
	v_cvt_pk_bf16_f32 v119, v230, v231
	v_cvt_pk_bf16_f32 v112, v232, v233
	v_cvt_pk_bf16_f32 v113, v234, v235
	v_cvt_pk_bf16_f32 v114, v236, v237
	v_cvt_pk_bf16_f32 v115, v238, v239
	s_nop 0
	v_permlane32_swap_b32_e32 v204, v205
	v_permlane32_swap_b32_e32 v112, v114
	v_permlane32_swap_b32_e32 v113, v115
	v_cvt_pk_bf16_f32 v120, v206, v207
	v_cvt_pk_bf16_f32 v121, v240, v241
	v_cvt_pk_bf16_f32 v122, v242, v243
	v_cvt_pk_bf16_f32 v123, v244, v10
	v_cvt_pk_bf16_f32 v124, v11, v12
	v_cvt_pk_bf16_f32 v125, v13, v144
	v_cvt_pk_bf16_f32 v126, v145, v146
	v_cvt_pk_bf16_f32 v127, v6, v7
	v_permlane32_swap_b32_e32 v117, v119
	v_permlane32_swap_b32_e32 v120, v122
	v_permlane32_swap_b32_e32 v121, v123
	v_permlane32_swap_b32_e32 v124, v126
	v_permlane32_swap_b32_e32 v125, v127
	v_add_u32_e32 v230, s59, v175
	ds_read_b64_tr_b16 v[2:3], v230 offset:0
	ds_read_b64_tr_b16 v[4:5], v230 offset:0x800
	ds_read_b64_tr_b16 v[6:7], v230 offset:0x1000
	ds_read_b64_tr_b16 v[8:9], v230 offset:0x1800
	ds_read_b64_tr_b16 v[10:11], v230 offset:0x2000
	ds_read_b64_tr_b16 v[12:13], v230 offset:0x2800
	ds_read_b64_tr_b16 v[144:145], v230 offset:0x3000
	ds_read_b64_tr_b16 v[146:147], v230 offset:0x3800
	s_add_i32 s58, s58, 2
	s_waitcnt lgkmcnt(0)
; __device__ __forceinline__ void pv_d0(f32x16* o, int vb, bf16x8 pa0, bf16x8 pa1, bf16x8 pa2, bf16x8 pa3) {
;   s16x4 la[4], ha[4];
;   rd8<0>(la, ha, vb); WAITDEP(0, la, ha); mma4(o[0], la, ha, pa0, pa1, pa2, pa3);
;   rd8<1>(la, ha, vb); WAITDEP(0, la, ha); mma4(o[1], la, ha, pa0, pa1, pa2, pa3);
;   rd8<2>(la, ha, vb); WAITDEP(0, la, ha); mma4(o[2], la, ha, pa0, pa1, pa2, pa3);
;   rd8<3>(la, ha, vb); WAITDEP(0, la, ha); mma4(o[3], la, ha, pa0, pa1, pa2, pa3);
; }
; template <int MODE>
; __device__ __forceinline__ void attn_unit(bf16r* P0, const bf16r* __restrict__ PKV, int rowbase, int seqL, int h, int blk, float lam,
;                                           const float* __restrict__ subg, const float* __restrict__ tsrc, char* lds) {
;   constexpr int NQ = (MODE == 0) ? 4 : 8;
;   int tid_ = threadIdx.x; asm volatile("" : "+v"(tid_));
;   const int tid = tid_, wid = __builtin_amdgcn_readfirstlane(tid >> 6), lane = tid & 63, r32 = lane & 31, hi = lane >> 5;
;   float* ws = (float*)(lds + OFF_WS) + wid * 64; float* li_l = ws; float* al_l = ws + 32;
;   float* tb = (float*)(lds + OFF_TB);
;   int qrow, kcolB, tbase, NT, colbase, gr = 0, rs = 0, qc = 0, cmap = 0;
;   float bL = 0.f, bR = 0.f;
;   if constexpr (MODE == 0) {
;     cmap = wid >> 2; qrow = blk * 128 + (wid & 3) * 32; kcolB = cmap * 128; tbase = 0; NT = seqL / KVBLK; colbase = h * 128;
;     bL = tsrc[15 * 8 + h] * LOG2E; bR = tsrc[31 * 8 + h] * LOG2E;
;     { const int rel = tid - 256, n = rel < 0 ? -rel : rel;
;       int bk = n < 8 ? n : min(15, 8 + (31 - __clz((n * n) >> 6))); if (rel > 0) bk += 16;
;       tb[tid] = tsrc[bk * 8 + h] * LOG2E; }
;   } else {
;     const int rows = seqL / 64; qrow = blk * 256 + wid * 32; kcolB = 0; colbase = 1024 + h * 128; NT = 12;
;     const int rs0 = min(max(blk * 4 - 4, 0), rows - 8); tbase = min(rs0, rows - 12);
;     gr = blk * 4 + (wid >> 1); rs = min(max(gr - 4, 0), rows - 8); qc = (wid & 1) * 32 + r32;
;     for (int i = tid; i < 15 * 128; i += 512) { const int dr = i >> 7, dc = (i & 127) - 48; tb[i] = (dc >= 0 && dc < 31) ? tsrc[(h * 15 + dr) * 31 + dc] * LOG2E : 0.f; }
;   }
;   const bf16r* Qw = P0 + (size_t)(rowbase + qrow + r32) * LD + colbase + (MODE == 0 ? cmap * 64 : 0) + hi * 8;
;   const bf16r* Kh = PKV + (size_t)rowbase * LD + h * 128; const bf16r* Vh = Kh + 1024;
;   float m_reg = -1e30f, l_reg = 0; f32x16 o[4] = {};
	s_add_i32 s34, s36, 0
	v_mfma_f32_32x32x16_bf16 v[64:79], v[116:119], v[2:5], v[64:79]
	ds_read_b64_tr_b16 v[2:3], v230 offset:0x200
	ds_read_b64_tr_b16 v[4:5], v230 offset:0xa00
	ds_read_b64_tr_b16 v[206:207], v230 offset:0x1200
	ds_read_b64_tr_b16 v[208:209], v230 offset:0x1a00
	ds_read_b64_tr_b16 v[210:211], v230 offset:0x2200
	ds_read_b64_tr_b16 v[212:213], v230 offset:0x2a00
	ds_read_b64_tr_b16 v[214:215], v230 offset:0x3200
	v_mfma_f32_32x32x16_bf16 v[64:79], v[112:115], v[6:9], v[64:79]
	ds_read_b64_tr_b16 v[216:217], v230 offset:0x3a00
	s_min_i32 s35, s58, s39
	s_waitcnt lgkmcnt(0)
	s_cmp_ge_i32 s35, s56
	s_cselect_b32 s60, s57, 0
	s_add_i32 s60, s60, s35
	s_lshl_b32 s35, s60, 6
	v_mfma_f32_32x32x16_bf16 v[48:63], v[116:119], v[2:5], v[48:63]
	ds_read_b64_tr_b16 v[2:3], v230 offset:0x400
	ds_read_b64_tr_b16 v[4:5], v230 offset:0xc00
	ds_read_b64_tr_b16 v[6:7], v230 offset:0x1400
	ds_read_b64_tr_b16 v[8:9], v230 offset:0x1c00
	v_mfma_f32_32x32x16_bf16 v[64:79], v[120:123], v[10:13], v[64:79]
	ds_read_b64_tr_b16 v[10:11], v230 offset:0x2400
	ds_read_b64_tr_b16 v[12:13], v230 offset:0x2c00
	v_mfma_f32_32x32x16_bf16 v[48:63], v[112:115], v[206:209], v[48:63]
	ds_read_b64_tr_b16 v[206:207], v230 offset:0x3400
	ds_read_b64_tr_b16 v[208:209], v230 offset:0x3c00
	s_nop 0
	s_waitcnt lgkmcnt(0)
	ds_read_b64_tr_b16 v[218:219], v230 offset:0x600
	ds_read_b64_tr_b16 v[220:221], v230 offset:0xe00
	s_nop 0
	v_mfma_f32_32x32x16_bf16 v[32:47], v[116:119], v[2:5], v[32:47]
	s_lshl_b32 s98, s35, 12
	s_add_u32 s98, s30, s98
	s_addc_u32 s99, s31, 0
	v_mfma_f32_32x32x16_bf16 v[48:63], v[120:123], v[210:213], v[48:63]
	ds_read_b64_tr_b16 v[210:211], v230 offset:0x1600
	ds_read_b64_tr_b16 v[212:213], v230 offset:0x1e00
	ds_read_b64_tr_b16 v[222:223], v230 offset:0x2600
	ds_read_b64_tr_b16 v[224:225], v230 offset:0x2e00
	ds_read_b64_tr_b16 v[226:227], v230 offset:0x3600
	ds_read_b64_tr_b16 v[228:229], v230 offset:0x3e00
	v_mfma_f32_32x32x16_bf16 v[32:47], v[112:115], v[6:9], v[32:47]
	s_waitcnt lgkmcnt(0)
	s_waitcnt vmcnt(0)
	v_mfma_f32_32x32x16_bf16 v[48:63], v[124:127], v[214:217], v[48:63]
	global_load_dwordx4 v[6:9], v252, s[98:99] offset:2048
	s_nop 0
	global_load_dwordx4 v[2:5], v252, s[98:99]
	v_mfma_f32_32x32x16_bf16 v[64:79], v[124:127], v[144:147], v[64:79]
	v_mfma_f32_32x32x16_bf16 v[32:47], v[120:123], v[10:13], v[32:47]
	global_load_dwordx4 v[144:147], v253, s[98:99] offset:2048
	global_load_dwordx4 v[10:13], v253, s[98:99]
	v_add_u32_e32 v214, s34, v183
	ds_write_b128 v214, v[156:159]
	v_add_u32_e32 v156, s34, v189
	ds_write_b128 v156, v[160:163]
	v_add_u32_e32 v156, s34, v190
	ds_write_b128 v156, v[148:151] offset:16384
	v_mfma_f32_32x32x16_bf16 v[16:31], v[116:119], v[218:221], v[16:31]
	v_add_u32_e32 v148, s34, v191
	ds_write_b128 v148, v[152:155] offset:16384
	v_max_f32_e32 v148, v128, v129
	v_max3_f32 v148, v148, v130, v131
	v_max3_f32 v148, v148, v132, v133
	v_mfma_f32_32x32x16_bf16 v[16:31], v[112:115], v[210:213], v[16:31]
	v_max3_f32 v116, v148, v134, v135
	v_max3_f32 v116, v116, v136, v137
	v_max3_f32 v116, v116, v138, v139
	v_max3_f32 v116, v116, v140, v141
	v_max3_f32 v116, v116, v142, v143
	v_max3_f32 v116, v116, v96, v97
	v_max3_f32 v116, v116, v98, v99
	v_mfma_f32_32x32x16_bf16 v[16:31], v[120:123], v[222:225], v[16:31]
	v_max3_f32 v112, v116, v100, v101
	v_max3_f32 v112, v112, v102, v103
	v_max3_f32 v112, v112, v104, v105
	v_max3_f32 v112, v112, v106, v107
	v_max3_f32 v112, v112, v108, v109
	v_max3_f32 v112, v112, v110, v111
	v_mov_b32_e32 v113, v112
	v_mfma_f32_32x32x16_bf16 v[32:47], v[124:127], v[206:209], v[32:47]
	s_nop 0
	v_permlane32_swap_b32_e32 v112, v113
	v_max_f32_e32 v113, v112, v113
	v_cmp_ge_f32_e32 vcc, s49, v113
	s_cmp_eq_u64 vcc, exec
	v_mfma_f32_32x32x16_bf16 v[16:31], v[124:127], v[226:229], v[16:31]
	v_mov_b32_e32 v112, 1.0
	s_cbranch_scc0 .LBB0_230
	s_branch .LBB0_227
